# FFN up GEMM: the 64 sample-row tiles (tail round, 64 of 256 workgroups busy) are split 4 ways along K over all 256 workgroups; f32 partials to workspace, last arriver per tile (atomic counter) sums th
# baseline (speedup 1.0000x reference)
;     __host__ __device__ bool next(int i, Unit& u) const {
;         const long L = (long)i * G + c; if (L >= nwg) return false;
;         int wgid = (int)L; { const int q = nwg / NXCD, r = nwg % NXCD, xcd = wgid % NXCD, off = wgid / NXCD; wgid = (xcd < r ? xcd * (q + 1) : r * (q + 1) + (xcd - r) * q) + off; }
;         const int nig = WGM * nN, gid = wgid / nig, fm = gid * WGM, gsz = (nM - fm) < WGM ? (nM - fm) : WGM;
;         u.pm = fm + ((wgid % nig) % gsz); u.pn = (wgid % nig) / gsz; u.koff = 0; u.nt = nt0; return true;
.LBB0_1063:
	s_cmp_ge_i32 s52, s20
	s_cselect_b64 s[24:25], -1, 0
	s_cmp_lt_i32 s52, s21
	s_cselect_b64 s[4:5], -1, 0
	s_and_b64 s[4:5], s[24:25], s[4:5]
	s_andn2_b64 vcc, exec, s[4:5]
	v_readlane_b32 s4, v255, 8
	v_readlane_b32 s5, v255, 9
	s_mov_b64 s[40:41], 0x3000000
	s_mov_b64 s[54:55], 0x3800000
	v_cndmask_b32_e64 v0, 0, 1, s[4:5]
	v_cmp_ne_u32_e64 s[6:7], 1, v0
	s_mov_b64 s[70:71], 0x3400000
	s_mov_b64 s[76:77], 0x3c00000
	s_cbranch_vccnz .LBB0_1118
	v_mov_b32_e32 v0, v218
	s_mov_b32 s10, s85
	s_mov_b64 s[8:9], s[0:1]
	s_waitcnt vmcnt(0)
	v_mov_b32_e32 v14, v218
	s_and_b64 vcc, exec, s[6:7]
	v_readfirstlane_b32 s14, v14
	s_cbranch_vccnz .LBB0_1066
	v_readlane_b32 s5, v255, 27
	v_readlane_b32 s4, v255, 26
	s_mov_b32 s12, s5
	s_and_b32 s4, s2, 7
	s_lshl_b32 s4, s4, 7
	s_lshr_b32 s5, s2, 3
	s_add_i32 s5, s4, s5
	s_lshr_b32 s4, s5, 8
	s_lshl_b32 s4, s4, 3
	s_and_b32 s12, s5, 7
	s_add_i32 s12, s12, s4
	s_bfe_u32 s4, s5, 0x50003

;     __host__ __device__ bool next(int i, Unit& u) const {
;         const long L = (long)i * G + c; if (L >= nwg) return false;
;         int wgid = (int)L; { const int q = nwg / NXCD, r = nwg % NXCD, xcd = wgid % NXCD, off = wgid / NXCD; wgid = (xcd < r ? xcd * (q + 1) : r * (q + 1) + (xcd - r) * q) + off; }
;         const int nig = WGM * nN, gid = wgid / nig, fm = gid * WGM, gsz = (nM - fm) < WGM ? (nM - fm) : WGM;
;         u.pm = fm + ((wgid % nig) % gsz); u.pn = (wgid % nig) / gsz; u.koff = 0; u.nt = nt0; return true;
; template <class Epi, class Sched, bool ALIGN_EPI = false, bool SP2 = false>
; __device__ __forceinline__ void gemm_phase(PG8_LAS unsigned char* lds, const Gemm g, const Sched& S, const Epi& E) {
;     ...
;         for (int a = 0; a < 2; ++a)
; #pragma unroll
;             for (int b = 0; b < 2; ++b)
; #pragma unroll
;                 for (int m = 0; m < 4; ++m)
; #pragma unroll
;                     for (int n = 0; n < 2; ++n) acc[a][b][m][n] = (f32x4){0.f, 0.f, 0.f, 0.f};
.LBB0_1072:
	s_add_i32 s76, s76, 1
	s_mul_i32 s5, s76, s29
	s_mul_hi_u32 s10, s76, s28
	s_add_i32 s10, s10, s5
	s_mul_i32 s5, s76, s28
	s_add_u32 s14, s5, s2
	s_addc_u32 s15, s10, s23
	s_mov_b32 s100, 0
	s_cmpk_lt_i32 s14, 0x400
	s_cbranch_scc1 .Lup_sched_norm
	s_cmpk_lt_i32 s14, 0x500
	s_cbranch_scc1 .Lup_sched_split
	s_mov_b64 s[10:11], 0
	s_branch .LBB0_1074
.Lup_sched_split:
	s_sub_i32 s5, s14, 0x400
	s_and_b32 s100, s5, 3
	s_lshl_b32 s100, s100, 10
	s_lshr_b32 s5, s5, 2
	s_and_b32 s56, s5, 31
	s_lshr_b32 s5, s5, 5
	s_add_i32 s58, s5, 32
	s_mov_b64 s[10:11], -1
	s_branch .LBB0_1074
.Lup_sched_norm:
	s_and_b32 s5, s14, 7
	s_lshl_b32 s5, s5, 7
	s_lshr_b32 s13, s14, 3
	s_add_i32 s5, s5, s13
	s_lshr_b32 s13, s5, 8
	s_lshl_b32 s13, s13, 3
	s_and_b32 s58, s5, 7
	s_add_i32 s58, s58, s13
	s_bfe_u32 s56, s5, 0x50003
	s_mov_b64 s[10:11], -1
	s_branch .LBB0_1074
.Lup_sched_dead:
	v_mov_b64_e32 v[0:1], 0x440
	v_cmp_lt_i64_e64 s[10:11], s[14:15], v[0:1]
	v_mov_b64_e32 v[0:1], 0x43f
	v_cmp_gt_i64_e32 vcc, s[14:15], v[0:1]
	s_cbranch_vccnz .LBB0_1074
	s_ashr_i32 s5, s14, 31
	s_lshr_b32 s5, s5, 29
	s_add_i32 s5, s14, s5
	s_ashr_i32 s13, s5, 3
	s_and_b32 s5, s5, -8
	s_sub_i32 s5, s14, s5
	s_cmp_lt_i32 s5, 0
	s_movk_i32 s14, 0x89
	s_cselect_b32 s14, s14, 0x88
	s_mul_i32 s5, s5, s14
	s_add_i32 s5, s5, s13
	s_ashr_i32 s13, s5, 31
	s_lshr_b32 s13, s13, 24
	s_add_i32 s13, s5, s13
	s_ashr_i32 s14, s13, 8
	s_lshl_b32 s14, s14, 3
	s_sub_i32 s15, 34, s14
	s_min_i32 s15, s15, 8
	s_abs_i32 s38, s15
	v_cvt_f32_u32_e32 v0, s38
	s_sub_i32 s46, 0, s38
	s_and_b32 s13, s13, 0xffffff00
	s_sub_i32 s5, s5, s13
	v_rcp_iflag_f32_e32 v0, v0
	s_abs_i32 s13, s5
	s_xor_b32 s39, s5, s15
	s_ashr_i32 s39, s39, 31
	v_mul_f32_e32 v0, 0x4f7ffffe, v0
	v_cvt_u32_f32_e32 v0, v0
	s_nop 0
	v_readfirstlane_b32 s47, v0
	s_mul_i32 s46, s46, s47
	s_mul_hi_u32 s46, s47, s46
	s_add_i32 s47, s47, s46
	s_mul_hi_u32 s46, s13, s47
	s_mul_i32 s47, s46, s38
	s_sub_i32 s13, s13, s47
	s_add_i32 s48, s46, 1
	s_sub_i32 s47, s13, s38
	s_cmp_ge_u32 s13, s38
	s_cselect_b32 s46, s48, s46
	s_cselect_b32 s13, s47, s13
	s_add_i32 s47, s46, 1
	s_cmp_ge_u32 s13, s38
	s_cselect_b32 s13, s47, s46
	s_xor_b32 s13, s13, s39
	s_sub_i32 s56, s13, s39
	s_mul_i32 s13, s56, s15
	s_sub_i32 s5, s5, s13
	s_add_i32 s58, s14, s5
.LBB0_1074:
	s_ashr_i32 s59, s58, 31
	s_lshl_b64 s[14:15], s[58:59], 20
	s_add_u32 s60, s53, s14
	s_addc_u32 s61, s54, s15
	s_add_u32 s60, s60, s100
	s_addc_u32 s61, s61, 0
	s_and_b64 s[14:15], s[10:11], exec
	s_cselect_b32 s5, s61, s37
	s_cselect_b32 s13, s60, s36
	s_ashr_i32 s57, s56, 31
	s_lshl_b64 s[14:15], s[56:57], 20
	s_add_u32 s62, s55, s14
	s_addc_u32 s63, s64, s15
	s_add_u32 s62, s62, s100
	s_addc_u32 s63, s63, 0
	s_and_b64 s[14:15], s[10:11], exec
	s_cselect_b32 s14, s63, s45
	s_cselect_b32 s15, s62, s44
	s_add_u32 s36, s36, 0x80080
	s_addc_u32 s37, s37, 0
	s_add_u32 s57, s44, 0x100
	v_mov_b32_e32 v0, 0
	s_addc_u32 s59, s45, 0
	s_mov_b32 s80, -2
	s_add_i32 s101, s76, -1
	s_mul_i32 s101, s101, s28
	s_add_i32 s101, s101, s2
	s_cmpk_lt_i32 s101, 0x400
	s_cbranch_scc1 .Lup_nt_norm
	s_mov_b32 s80, 22
.Lup_nt_norm:
	v_mov_b32_e32 v1, v0
	v_mov_b32_e32 v2, v0
	v_mov_b32_e32 v3, v0
	v_mov_b32_e32 v4, v0
	v_mov_b32_e32 v5, v0
	v_mov_b32_e32 v6, v0
	v_mov_b32_e32 v7, v0
	v_mov_b32_e32 v16, v0
	v_mov_b32_e32 v17, v0
	v_mov_b32_e32 v18, v0
	v_mov_b32_e32 v19, v0
	v_mov_b32_e32 v20, v0
	v_mov_b32_e32 v21, v0
	v_mov_b32_e32 v22, v0
	v_mov_b32_e32 v23, v0
	v_mov_b32_e32 v32, v0
	v_mov_b32_e32 v33, v0
	v_mov_b32_e32 v34, v0
	v_mov_b32_e32 v35, v0
	v_mov_b32_e32 v36, v0
	v_mov_b32_e32 v37, v0
	v_mov_b32_e32 v38, v0
	v_mov_b32_e32 v39, v0
	v_mov_b32_e32 v48, v0
	v_mov_b32_e32 v49, v0
	v_mov_b32_e32 v50, v0
	v_mov_b32_e32 v51, v0
	v_mov_b32_e32 v52, v0
	v_mov_b32_e32 v53, v0
	v_mov_b32_e32 v54, v0
	v_mov_b32_e32 v55, v0
	v_mov_b32_e32 v8, v0
	v_mov_b32_e32 v9, v0
	v_mov_b32_e32 v10, v0
	v_mov_b32_e32 v11, v0
	v_mov_b32_e32 v12, v0
	v_mov_b32_e32 v13, v0
	v_mov_b32_e32 v14, v0
	v_mov_b32_e32 v15, v0
	v_mov_b32_e32 v24, v0
	v_mov_b32_e32 v25, v0
	v_mov_b32_e32 v26, v0
	v_mov_b32_e32 v27, v0
	v_mov_b32_e32 v28, v0
	v_mov_b32_e32 v29, v0
	v_mov_b32_e32 v30, v0
	v_mov_b32_e32 v31, v0
	v_mov_b32_e32 v40, v0
	v_mov_b32_e32 v41, v0
	v_mov_b32_e32 v42, v0
	v_mov_b32_e32 v43, v0
	v_mov_b32_e32 v44, v0
	v_mov_b32_e32 v45, v0
	v_mov_b32_e32 v46, v0
	v_mov_b32_e32 v47, v0
	v_mov_b32_e32 v56, v0
	v_mov_b32_e32 v57, v0
	v_mov_b32_e32 v58, v0
	v_mov_b32_e32 v59, v0
	v_mov_b32_e32 v60, v0
	v_mov_b32_e32 v61, v0
	v_mov_b32_e32 v62, v0
	v_mov_b32_e32 v63, v0
	v_mov_b32_e32 v64, v0
	v_mov_b32_e32 v65, v0
	v_mov_b32_e32 v66, v0
	v_mov_b32_e32 v67, v0
	v_mov_b32_e32 v68, v0
	v_mov_b32_e32 v69, v0
	v_mov_b32_e32 v70, v0
	v_mov_b32_e32 v71, v0
	v_mov_b32_e32 v80, v0
	v_mov_b32_e32 v81, v0
	v_mov_b32_e32 v82, v0
	v_mov_b32_e32 v83, v0
	v_mov_b32_e32 v84, v0
	v_mov_b32_e32 v85, v0
	v_mov_b32_e32 v86, v0
	v_mov_b32_e32 v87, v0
	v_mov_b32_e32 v96, v0
	v_mov_b32_e32 v97, v0
	v_mov_b32_e32 v98, v0
	v_mov_b32_e32 v99, v0
	v_mov_b32_e32 v100, v0
	v_mov_b32_e32 v101, v0
	v_mov_b32_e32 v102, v0
	v_mov_b32_e32 v103, v0
	v_mov_b32_e32 v112, v0
	v_mov_b32_e32 v113, v0
	v_mov_b32_e32 v114, v0
	v_mov_b32_e32 v115, v0
	v_mov_b32_e32 v116, v0
	v_mov_b32_e32 v117, v0
	v_mov_b32_e32 v118, v0
	v_mov_b32_e32 v119, v0
	v_mov_b32_e32 v72, v0
	v_mov_b32_e32 v73, v0
	v_mov_b32_e32 v74, v0
	v_mov_b32_e32 v75, v0
	v_mov_b32_e32 v76, v0
	v_mov_b32_e32 v77, v0
	v_mov_b32_e32 v78, v0
	v_mov_b32_e32 v79, v0
	v_mov_b32_e32 v88, v0
	v_mov_b32_e32 v89, v0
	v_mov_b32_e32 v90, v0
	v_mov_b32_e32 v91, v0
	v_mov_b32_e32 v92, v0
	v_mov_b32_e32 v93, v0
	v_mov_b32_e32 v94, v0
	v_mov_b32_e32 v95, v0
	v_mov_b32_e32 v104, v0
	v_mov_b32_e32 v105, v0
	v_mov_b32_e32 v106, v0
	v_mov_b32_e32 v107, v0
	v_mov_b32_e32 v108, v0
	v_mov_b32_e32 v109, v0
	v_mov_b32_e32 v110, v0
	v_mov_b32_e32 v111, v0
	v_mov_b32_e32 v120, v0
	v_mov_b32_e32 v121, v0
	v_mov_b32_e32 v122, v0
	v_mov_b32_e32 v123, v0
	v_mov_b32_e32 v124, v0
	v_mov_b32_e32 v125, v0
	v_mov_b32_e32 v126, v0
	v_mov_b32_e32 v127, v0

; #define PG8_BAR __builtin_amdgcn_s_barrier()
; template <class Epi, class Sched, bool ALIGN_EPI = false, bool SP2 = false>
; __device__ __forceinline__ void gemm_phase(PG8_LAS unsigned char* lds, const Gemm g, const Sched& S, const Epi& E) {
;     ...
;         if constexpr (ALIGN_EPI) { if (wr == 0) PG8_BAR; }
;         if constexpr (!Epi::AFTER_DRAIN) { E(acc, cur, wr, wc, fr, fq); S.done(cur); }
.LBB0_1078:
	s_add_i32 s100, s76, -1
	s_mul_i32 s100, s100, s28
	s_add_i32 s100, s100, s2
	s_cmpk_lt_i32 s100, 0x400
	s_cbranch_scc1 .Lup_ep_normal
	s_sub_i32 s100, s100, 0x400
	s_lshl_b32 s101, s100, 18
	s_add_u32 s38, s18, 0x34e00000
	s_addc_u32 s39, s19, 0
	s_add_u32 s38, s38, s101
	s_addc_u32 s39, s39, 0
	v_lshlrev_b32_e32 v152, 4, v218
	global_store_dwordx4 v152, v[0:3], s[38:39]
	s_add_u32 s38, s38, 0x2000
	s_addc_u32 s39, s39, 0
	global_store_dwordx4 v152, v[4:7], s[38:39]
	s_add_u32 s38, s38, 0x2000
	s_addc_u32 s39, s39, 0
	global_store_dwordx4 v152, v[8:11], s[38:39]
	s_add_u32 s38, s38, 0x2000
	s_addc_u32 s39, s39, 0
	global_store_dwordx4 v152, v[12:15], s[38:39]
	s_add_u32 s38, s38, 0x2000
	s_addc_u32 s39, s39, 0
	global_store_dwordx4 v152, v[16:19], s[38:39]
	s_add_u32 s38, s38, 0x2000
	s_addc_u32 s39, s39, 0
	global_store_dwordx4 v152, v[20:23], s[38:39]
	s_add_u32 s38, s38, 0x2000
	s_addc_u32 s39, s39, 0
	global_store_dwordx4 v152, v[24:27], s[38:39]
	s_add_u32 s38, s38, 0x2000
	s_addc_u32 s39, s39, 0
	global_store_dwordx4 v152, v[28:31], s[38:39]
	s_add_u32 s38, s38, 0x2000
	s_addc_u32 s39, s39, 0
	global_store_dwordx4 v152, v[32:35], s[38:39]
	s_add_u32 s38, s38, 0x2000
	s_addc_u32 s39, s39, 0
	global_store_dwordx4 v152, v[36:39], s[38:39]
	s_add_u32 s38, s38, 0x2000
	s_addc_u32 s39, s39, 0
	global_store_dwordx4 v152, v[40:43], s[38:39]
	s_add_u32 s38, s38, 0x2000
	s_addc_u32 s39, s39, 0
	global_store_dwordx4 v152, v[44:47], s[38:39]
	s_add_u32 s38, s38, 0x2000
	s_addc_u32 s39, s39, 0
	global_store_dwordx4 v152, v[48:51], s[38:39]
	s_add_u32 s38, s38, 0x2000
	s_addc_u32 s39, s39, 0
	global_store_dwordx4 v152, v[52:55], s[38:39]
	s_add_u32 s38, s38, 0x2000
	s_addc_u32 s39, s39, 0
	global_store_dwordx4 v152, v[56:59], s[38:39]
	s_add_u32 s38, s38, 0x2000
	s_addc_u32 s39, s39, 0
	global_store_dwordx4 v152, v[60:63], s[38:39]
	s_add_u32 s38, s38, 0x2000
	s_addc_u32 s39, s39, 0
	global_store_dwordx4 v152, v[64:67], s[38:39]
	s_add_u32 s38, s38, 0x2000
	s_addc_u32 s39, s39, 0
	global_store_dwordx4 v152, v[68:71], s[38:39]
	s_add_u32 s38, s38, 0x2000
	s_addc_u32 s39, s39, 0
	global_store_dwordx4 v152, v[72:75], s[38:39]
	s_add_u32 s38, s38, 0x2000
	s_addc_u32 s39, s39, 0
	global_store_dwordx4 v152, v[76:79], s[38:39]
	s_add_u32 s38, s38, 0x2000
	s_addc_u32 s39, s39, 0
	global_store_dwordx4 v152, v[80:83], s[38:39]
	s_add_u32 s38, s38, 0x2000
	s_addc_u32 s39, s39, 0
	global_store_dwordx4 v152, v[84:87], s[38:39]
	s_add_u32 s38, s38, 0x2000
	s_addc_u32 s39, s39, 0
	global_store_dwordx4 v152, v[88:91], s[38:39]
	s_add_u32 s38, s38, 0x2000
	s_addc_u32 s39, s39, 0
	global_store_dwordx4 v152, v[92:95], s[38:39]
	s_add_u32 s38, s38, 0x2000
	s_addc_u32 s39, s39, 0
	global_store_dwordx4 v152, v[96:99], s[38:39]
	s_add_u32 s38, s38, 0x2000
	s_addc_u32 s39, s39, 0
	global_store_dwordx4 v152, v[100:103], s[38:39]
	s_add_u32 s38, s38, 0x2000
	s_addc_u32 s39, s39, 0
	global_store_dwordx4 v152, v[104:107], s[38:39]
	s_add_u32 s38, s38, 0x2000
	s_addc_u32 s39, s39, 0
	global_store_dwordx4 v152, v[108:111], s[38:39]
	s_add_u32 s38, s38, 0x2000
	s_addc_u32 s39, s39, 0
	global_store_dwordx4 v152, v[112:115], s[38:39]
	s_add_u32 s38, s38, 0x2000
	s_addc_u32 s39, s39, 0
	global_store_dwordx4 v152, v[116:119], s[38:39]
	s_add_u32 s38, s38, 0x2000
	s_addc_u32 s39, s39, 0
	global_store_dwordx4 v152, v[120:123], s[38:39]
	s_add_u32 s38, s38, 0x2000
	s_addc_u32 s39, s39, 0
	global_store_dwordx4 v152, v[124:127], s[38:39]
	s_add_u32 s38, s38, 0x2000
	s_addc_u32 s39, s39, 0
	s_waitcnt vmcnt(0)
	s_barrier
	v_cmp_eq_u32_e32 vcc, 0, v218
	s_and_saveexec_b64 s[46:47], vcc
	s_cbranch_execz .Lup_sk_atom
	buffer_wbl2 sc1
	s_waitcnt vmcnt(0)
	s_lshr_b32 s101, s100, 2
	s_lshl_b32 s101, s101, 2
	s_add_u32 s48, s18, 0x3600
	s_addc_u32 s49, s19, 0
	v_mov_b32_e32 v153, s101
	v_mov_b32_e32 v154, 1
	global_atomic_add v155, v153, v154, s[48:49] sc0
	s_waitcnt vmcnt(0)
	v_mov_b32_e32 v156, 0x23fe0
	ds_write_b32 v156, v155
	s_waitcnt lgkmcnt(0)
.Lup_sk_atom:
	s_mov_b64 exec, s[46:47]
	s_barrier
	v_mov_b32_e32 v156, 0x23fe0
	ds_read_b32 v155, v156
	s_waitcnt lgkmcnt(0)
	v_readfirstlane_b32 s101, v155
	s_nop 3
	s_and_b32 s101, s101, 3
	s_cmp_eq_u32 s101, 3
	s_cbranch_scc0 .Lup_ep_done
	buffer_inv sc1
	s_waitcnt vmcnt(0)
; #define PG8_BAR __builtin_amdgcn_s_barrier()
; template <class Epi, class Sched, bool ALIGN_EPI = false, bool SP2 = false>
; __device__ __forceinline__ void gemm_phase(PG8_LAS unsigned char* lds, const Gemm g, const Sched& S, const Epi& E) {
;     ...
;         if constexpr (ALIGN_EPI) { if (wr == 0) PG8_BAR; }
;         if constexpr (!Epi::AFTER_DRAIN) { E(acc, cur, wr, wc, fr, fq); S.done(cur); }
	s_and_b32 s100, s100, 0xfffffffc
	s_lshl_b32 s101, s100, 18
	s_add_u32 s38, s18, 0x34e00000
	s_addc_u32 s39, s19, 0
	s_add_u32 s38, s38, s101
	s_addc_u32 s39, s39, 0
	global_load_dwordx4 v[0:3], v152, s[38:39]
	s_add_u32 s38, s38, 0x2000
	s_addc_u32 s39, s39, 0
	global_load_dwordx4 v[4:7], v152, s[38:39]
	s_add_u32 s38, s38, 0x2000
	s_addc_u32 s39, s39, 0
	global_load_dwordx4 v[8:11], v152, s[38:39]
	s_add_u32 s38, s38, 0x2000
	s_addc_u32 s39, s39, 0
	global_load_dwordx4 v[12:15], v152, s[38:39]
	s_add_u32 s38, s38, 0x2000
	s_addc_u32 s39, s39, 0
	global_load_dwordx4 v[16:19], v152, s[38:39]
	s_add_u32 s38, s38, 0x2000
	s_addc_u32 s39, s39, 0
	global_load_dwordx4 v[20:23], v152, s[38:39]
	s_add_u32 s38, s38, 0x2000
	s_addc_u32 s39, s39, 0
	global_load_dwordx4 v[24:27], v152, s[38:39]
	s_add_u32 s38, s38, 0x2000
	s_addc_u32 s39, s39, 0
	global_load_dwordx4 v[28:31], v152, s[38:39]
	s_add_u32 s38, s38, 0x2000
	s_addc_u32 s39, s39, 0
	global_load_dwordx4 v[32:35], v152, s[38:39]
	s_add_u32 s38, s38, 0x2000
	s_addc_u32 s39, s39, 0
	global_load_dwordx4 v[36:39], v152, s[38:39]
	s_add_u32 s38, s38, 0x2000
	s_addc_u32 s39, s39, 0
	global_load_dwordx4 v[40:43], v152, s[38:39]
	s_add_u32 s38, s38, 0x2000
	s_addc_u32 s39, s39, 0
	global_load_dwordx4 v[44:47], v152, s[38:39]
	s_add_u32 s38, s38, 0x2000
	s_addc_u32 s39, s39, 0
	global_load_dwordx4 v[48:51], v152, s[38:39]
	s_add_u32 s38, s38, 0x2000
	s_addc_u32 s39, s39, 0
	global_load_dwordx4 v[52:55], v152, s[38:39]
	s_add_u32 s38, s38, 0x2000
	s_addc_u32 s39, s39, 0
	global_load_dwordx4 v[56:59], v152, s[38:39]
	s_add_u32 s38, s38, 0x2000
	s_addc_u32 s39, s39, 0
	global_load_dwordx4 v[60:63], v152, s[38:39]
	s_add_u32 s38, s38, 0x2000
	s_addc_u32 s39, s39, 0
	global_load_dwordx4 v[64:67], v152, s[38:39]
	s_add_u32 s38, s38, 0x2000
	s_addc_u32 s39, s39, 0
	global_load_dwordx4 v[68:71], v152, s[38:39]
	s_add_u32 s38, s38, 0x2000
	s_addc_u32 s39, s39, 0
	global_load_dwordx4 v[72:75], v152, s[38:39]
	s_add_u32 s38, s38, 0x2000
	s_addc_u32 s39, s39, 0
	global_load_dwordx4 v[76:79], v152, s[38:39]
	s_add_u32 s38, s38, 0x2000
	s_addc_u32 s39, s39, 0
	global_load_dwordx4 v[80:83], v152, s[38:39]
	s_add_u32 s38, s38, 0x2000
	s_addc_u32 s39, s39, 0
	global_load_dwordx4 v[84:87], v152, s[38:39]
	s_add_u32 s38, s38, 0x2000
	s_addc_u32 s39, s39, 0
	global_load_dwordx4 v[88:91], v152, s[38:39]
	s_add_u32 s38, s38, 0x2000
	s_addc_u32 s39, s39, 0
	global_load_dwordx4 v[92:95], v152, s[38:39]
	s_add_u32 s38, s38, 0x2000
	s_addc_u32 s39, s39, 0
	global_load_dwordx4 v[96:99], v152, s[38:39]
	s_add_u32 s38, s38, 0x2000
	s_addc_u32 s39, s39, 0
	global_load_dwordx4 v[100:103], v152, s[38:39]
	s_add_u32 s38, s38, 0x2000
	s_addc_u32 s39, s39, 0
	global_load_dwordx4 v[104:107], v152, s[38:39]
	s_add_u32 s38, s38, 0x2000
	s_addc_u32 s39, s39, 0
	global_load_dwordx4 v[108:111], v152, s[38:39]
	s_add_u32 s38, s38, 0x2000
	s_addc_u32 s39, s39, 0
	global_load_dwordx4 v[112:115], v152, s[38:39]
	s_add_u32 s38, s38, 0x2000
	s_addc_u32 s39, s39, 0
	global_load_dwordx4 v[116:119], v152, s[38:39]
	s_add_u32 s38, s38, 0x2000
	s_addc_u32 s39, s39, 0
	global_load_dwordx4 v[120:123], v152, s[38:39]
	s_add_u32 s38, s38, 0x2000
	s_addc_u32 s39, s39, 0
	global_load_dwordx4 v[124:127], v152, s[38:39]
	s_add_u32 s38, s38, 0x2000
	s_addc_u32 s39, s39, 0
	global_load_dwordx4 v[160:163], v152, s[38:39]
	s_add_u32 s38, s38, 0x2000
	s_addc_u32 s39, s39, 0
	global_load_dwordx4 v[164:167], v152, s[38:39]
	s_add_u32 s38, s38, 0x2000
	s_addc_u32 s39, s39, 0
	global_load_dwordx4 v[168:171], v152, s[38:39]
	s_add_u32 s38, s38, 0x2000
	s_addc_u32 s39, s39, 0
	global_load_dwordx4 v[172:175], v152, s[38:39]
	s_add_u32 s38, s38, 0x2000
	s_addc_u32 s39, s39, 0
	global_load_dwordx4 v[176:179], v152, s[38:39]
	s_add_u32 s38, s38, 0x2000
	s_addc_u32 s39, s39, 0
	global_load_dwordx4 v[180:183], v152, s[38:39]
	s_add_u32 s38, s38, 0x2000
	s_addc_u32 s39, s39, 0
	global_load_dwordx4 v[184:187], v152, s[38:39]
	s_add_u32 s38, s38, 0x2000
	s_addc_u32 s39, s39, 0
	global_load_dwordx4 v[188:191], v152, s[38:39]
	s_add_u32 s38, s38, 0x2000
	s_addc_u32 s39, s39, 0
	global_load_dwordx4 v[198:201], v152, s[38:39]
	s_add_u32 s38, s38, 0x2000
	s_addc_u32 s39, s39, 0
	global_load_dwordx4 v[202:205], v152, s[38:39]
	s_add_u32 s38, s38, 0x2000
	s_addc_u32 s39, s39, 0
	global_load_dwordx4 v[206:209], v152, s[38:39]
	s_add_u32 s38, s38, 0x2000
	s_addc_u32 s39, s39, 0
	s_waitcnt vmcnt(0)
; #define PG8_BAR __builtin_amdgcn_s_barrier()
; template <class Epi, class Sched, bool ALIGN_EPI = false, bool SP2 = false>
; __device__ __forceinline__ void gemm_phase(PG8_LAS unsigned char* lds, const Gemm g, const Sched& S, const Epi& E) {
;     ...
;         if constexpr (ALIGN_EPI) { if (wr == 0) PG8_BAR; }
;         if constexpr (!Epi::AFTER_DRAIN) { E(acc, cur, wr, wc, fr, fq); S.done(cur); }
	v_add_f32_e32 v0, v0, v160
	v_add_f32_e32 v1, v1, v161
	v_add_f32_e32 v2, v2, v162
	v_add_f32_e32 v3, v3, v163
	v_add_f32_e32 v4, v4, v164
	v_add_f32_e32 v5, v5, v165
	v_add_f32_e32 v6, v6, v166
	v_add_f32_e32 v7, v7, v167
	v_add_f32_e32 v8, v8, v168
	v_add_f32_e32 v9, v9, v169
	v_add_f32_e32 v10, v10, v170
	v_add_f32_e32 v11, v11, v171
	v_add_f32_e32 v12, v12, v172
	v_add_f32_e32 v13, v13, v173
	v_add_f32_e32 v14, v14, v174
	v_add_f32_e32 v15, v15, v175
	v_add_f32_e32 v16, v16, v176
	v_add_f32_e32 v17, v17, v177
	v_add_f32_e32 v18, v18, v178
	v_add_f32_e32 v19, v19, v179
	v_add_f32_e32 v20, v20, v180
	v_add_f32_e32 v21, v21, v181
	v_add_f32_e32 v22, v22, v182
	v_add_f32_e32 v23, v23, v183
	v_add_f32_e32 v24, v24, v184
	v_add_f32_e32 v25, v25, v185
	v_add_f32_e32 v26, v26, v186
	v_add_f32_e32 v27, v27, v187
	v_add_f32_e32 v28, v28, v188
	v_add_f32_e32 v29, v29, v189
	v_add_f32_e32 v30, v30, v190
	v_add_f32_e32 v31, v31, v191
	v_add_f32_e32 v32, v32, v198
	v_add_f32_e32 v33, v33, v199
	v_add_f32_e32 v34, v34, v200
	v_add_f32_e32 v35, v35, v201
	v_add_f32_e32 v36, v36, v202
	v_add_f32_e32 v37, v37, v203
	v_add_f32_e32 v38, v38, v204
	v_add_f32_e32 v39, v39, v205
	v_add_f32_e32 v40, v40, v206
	v_add_f32_e32 v41, v41, v207
	v_add_f32_e32 v42, v42, v208
	v_add_f32_e32 v43, v43, v209
	global_load_dwordx4 v[160:163], v152, s[38:39]
	s_add_u32 s38, s38, 0x2000
	s_addc_u32 s39, s39, 0
	global_load_dwordx4 v[164:167], v152, s[38:39]
	s_add_u32 s38, s38, 0x2000
	s_addc_u32 s39, s39, 0
	global_load_dwordx4 v[168:171], v152, s[38:39]
	s_add_u32 s38, s38, 0x2000
	s_addc_u32 s39, s39, 0
	global_load_dwordx4 v[172:175], v152, s[38:39]
	s_add_u32 s38, s38, 0x2000
	s_addc_u32 s39, s39, 0
	global_load_dwordx4 v[176:179], v152, s[38:39]
	s_add_u32 s38, s38, 0x2000
	s_addc_u32 s39, s39, 0
	global_load_dwordx4 v[180:183], v152, s[38:39]
	s_add_u32 s38, s38, 0x2000
	s_addc_u32 s39, s39, 0
	global_load_dwordx4 v[184:187], v152, s[38:39]
	s_add_u32 s38, s38, 0x2000
	s_addc_u32 s39, s39, 0
	global_load_dwordx4 v[188:191], v152, s[38:39]
	s_add_u32 s38, s38, 0x2000
	s_addc_u32 s39, s39, 0
	global_load_dwordx4 v[198:201], v152, s[38:39]
	s_add_u32 s38, s38, 0x2000
	s_addc_u32 s39, s39, 0
	global_load_dwordx4 v[202:205], v152, s[38:39]
	s_add_u32 s38, s38, 0x2000
	s_addc_u32 s39, s39, 0
	global_load_dwordx4 v[206:209], v152, s[38:39]
	s_add_u32 s38, s38, 0x2000
	s_addc_u32 s39, s39, 0
	s_waitcnt vmcnt(0)
	v_add_f32_e32 v44, v44, v160
	v_add_f32_e32 v45, v45, v161
	v_add_f32_e32 v46, v46, v162
	v_add_f32_e32 v47, v47, v163
	v_add_f32_e32 v48, v48, v164
	v_add_f32_e32 v49, v49, v165
	v_add_f32_e32 v50, v50, v166
	v_add_f32_e32 v51, v51, v167
	v_add_f32_e32 v52, v52, v168
	v_add_f32_e32 v53, v53, v169
	v_add_f32_e32 v54, v54, v170
	v_add_f32_e32 v55, v55, v171
	v_add_f32_e32 v56, v56, v172
	v_add_f32_e32 v57, v57, v173
	v_add_f32_e32 v58, v58, v174
	v_add_f32_e32 v59, v59, v175
	v_add_f32_e32 v60, v60, v176
	v_add_f32_e32 v61, v61, v177
	v_add_f32_e32 v62, v62, v178
	v_add_f32_e32 v63, v63, v179
	v_add_f32_e32 v64, v64, v180
	v_add_f32_e32 v65, v65, v181
	v_add_f32_e32 v66, v66, v182
	v_add_f32_e32 v67, v67, v183
	v_add_f32_e32 v68, v68, v184
	v_add_f32_e32 v69, v69, v185
	v_add_f32_e32 v70, v70, v186
	v_add_f32_e32 v71, v71, v187
	v_add_f32_e32 v72, v72, v188
	v_add_f32_e32 v73, v73, v189
	v_add_f32_e32 v74, v74, v190
	v_add_f32_e32 v75, v75, v191
	v_add_f32_e32 v76, v76, v198
	v_add_f32_e32 v77, v77, v199
	v_add_f32_e32 v78, v78, v200
	v_add_f32_e32 v79, v79, v201
	v_add_f32_e32 v80, v80, v202
	v_add_f32_e32 v81, v81, v203
	v_add_f32_e32 v82, v82, v204
	v_add_f32_e32 v83, v83, v205
	v_add_f32_e32 v84, v84, v206
	v_add_f32_e32 v85, v85, v207
	v_add_f32_e32 v86, v86, v208
	v_add_f32_e32 v87, v87, v209
	global_load_dwordx4 v[160:163], v152, s[38:39]
	s_add_u32 s38, s38, 0x2000
	s_addc_u32 s39, s39, 0
	global_load_dwordx4 v[164:167], v152, s[38:39]
	s_add_u32 s38, s38, 0x2000
	s_addc_u32 s39, s39, 0
	global_load_dwordx4 v[168:171], v152, s[38:39]
	s_add_u32 s38, s38, 0x2000
	s_addc_u32 s39, s39, 0
	global_load_dwordx4 v[172:175], v152, s[38:39]
	s_add_u32 s38, s38, 0x2000
	s_addc_u32 s39, s39, 0
	global_load_dwordx4 v[176:179], v152, s[38:39]
	s_add_u32 s38, s38, 0x2000
	s_addc_u32 s39, s39, 0
	global_load_dwordx4 v[180:183], v152, s[38:39]
	s_add_u32 s38, s38, 0x2000
	s_addc_u32 s39, s39, 0
	global_load_dwordx4 v[184:187], v152, s[38:39]
	s_add_u32 s38, s38, 0x2000
	s_addc_u32 s39, s39, 0
	global_load_dwordx4 v[188:191], v152, s[38:39]
	s_add_u32 s38, s38, 0x2000
	s_addc_u32 s39, s39, 0
	global_load_dwordx4 v[198:201], v152, s[38:39]
	s_add_u32 s38, s38, 0x2000
	s_addc_u32 s39, s39, 0
	global_load_dwordx4 v[202:205], v152, s[38:39]
	s_add_u32 s38, s38, 0x2000
	s_addc_u32 s39, s39, 0
	s_waitcnt vmcnt(0)
; #define PG8_BAR __builtin_amdgcn_s_barrier()
; template <class Epi, class Sched, bool ALIGN_EPI = false, bool SP2 = false>
; __device__ __forceinline__ void gemm_phase(PG8_LAS unsigned char* lds, const Gemm g, const Sched& S, const Epi& E) {
;     ...
;         if constexpr (ALIGN_EPI) { if (wr == 0) PG8_BAR; }
;         if constexpr (!Epi::AFTER_DRAIN) { E(acc, cur, wr, wc, fr, fq); S.done(cur); }
	v_add_f32_e32 v88, v88, v160
	v_add_f32_e32 v89, v89, v161
	v_add_f32_e32 v90, v90, v162
	v_add_f32_e32 v91, v91, v163
	v_add_f32_e32 v92, v92, v164
	v_add_f32_e32 v93, v93, v165
	v_add_f32_e32 v94, v94, v166
	v_add_f32_e32 v95, v95, v167
	v_add_f32_e32 v96, v96, v168
	v_add_f32_e32 v97, v97, v169
	v_add_f32_e32 v98, v98, v170
	v_add_f32_e32 v99, v99, v171
	v_add_f32_e32 v100, v100, v172
	v_add_f32_e32 v101, v101, v173
	v_add_f32_e32 v102, v102, v174
	v_add_f32_e32 v103, v103, v175
	v_add_f32_e32 v104, v104, v176
	v_add_f32_e32 v105, v105, v177
	v_add_f32_e32 v106, v106, v178
	v_add_f32_e32 v107, v107, v179
	v_add_f32_e32 v108, v108, v180
	v_add_f32_e32 v109, v109, v181
	v_add_f32_e32 v110, v110, v182
	v_add_f32_e32 v111, v111, v183
	v_add_f32_e32 v112, v112, v184
	v_add_f32_e32 v113, v113, v185
	v_add_f32_e32 v114, v114, v186
	v_add_f32_e32 v115, v115, v187
	v_add_f32_e32 v116, v116, v188
	v_add_f32_e32 v117, v117, v189
	v_add_f32_e32 v118, v118, v190
	v_add_f32_e32 v119, v119, v191
	v_add_f32_e32 v120, v120, v198
	v_add_f32_e32 v121, v121, v199
	v_add_f32_e32 v122, v122, v200
	v_add_f32_e32 v123, v123, v201
	v_add_f32_e32 v124, v124, v202
	v_add_f32_e32 v125, v125, v203
	v_add_f32_e32 v126, v126, v204
	v_add_f32_e32 v127, v127, v205
	global_load_dwordx4 v[160:163], v152, s[38:39]
	s_add_u32 s38, s38, 0x2000
	s_addc_u32 s39, s39, 0
	global_load_dwordx4 v[164:167], v152, s[38:39]
	s_add_u32 s38, s38, 0x2000
	s_addc_u32 s39, s39, 0
	global_load_dwordx4 v[168:171], v152, s[38:39]
	s_add_u32 s38, s38, 0x2000
	s_addc_u32 s39, s39, 0
	global_load_dwordx4 v[172:175], v152, s[38:39]
	s_add_u32 s38, s38, 0x2000
	s_addc_u32 s39, s39, 0
	global_load_dwordx4 v[176:179], v152, s[38:39]
	s_add_u32 s38, s38, 0x2000
	s_addc_u32 s39, s39, 0
	global_load_dwordx4 v[180:183], v152, s[38:39]
	s_add_u32 s38, s38, 0x2000
	s_addc_u32 s39, s39, 0
	global_load_dwordx4 v[184:187], v152, s[38:39]
	s_add_u32 s38, s38, 0x2000
	s_addc_u32 s39, s39, 0
	global_load_dwordx4 v[188:191], v152, s[38:39]
	s_add_u32 s38, s38, 0x2000
	s_addc_u32 s39, s39, 0
	global_load_dwordx4 v[198:201], v152, s[38:39]
	s_add_u32 s38, s38, 0x2000
	s_addc_u32 s39, s39, 0
	global_load_dwordx4 v[202:205], v152, s[38:39]
	s_add_u32 s38, s38, 0x2000
	s_addc_u32 s39, s39, 0
	global_load_dwordx4 v[206:209], v152, s[38:39]
	s_add_u32 s38, s38, 0x2000
	s_addc_u32 s39, s39, 0
	s_waitcnt vmcnt(0)
	v_add_f32_e32 v0, v0, v160
	v_add_f32_e32 v1, v1, v161
	v_add_f32_e32 v2, v2, v162
	v_add_f32_e32 v3, v3, v163
	v_add_f32_e32 v4, v4, v164
	v_add_f32_e32 v5, v5, v165
	v_add_f32_e32 v6, v6, v166
	v_add_f32_e32 v7, v7, v167
	v_add_f32_e32 v8, v8, v168
	v_add_f32_e32 v9, v9, v169
	v_add_f32_e32 v10, v10, v170
	v_add_f32_e32 v11, v11, v171
	v_add_f32_e32 v12, v12, v172
	v_add_f32_e32 v13, v13, v173
	v_add_f32_e32 v14, v14, v174
	v_add_f32_e32 v15, v15, v175
	v_add_f32_e32 v16, v16, v176
	v_add_f32_e32 v17, v17, v177
	v_add_f32_e32 v18, v18, v178
	v_add_f32_e32 v19, v19, v179
	v_add_f32_e32 v20, v20, v180
	v_add_f32_e32 v21, v21, v181
	v_add_f32_e32 v22, v22, v182
	v_add_f32_e32 v23, v23, v183
	v_add_f32_e32 v24, v24, v184
	v_add_f32_e32 v25, v25, v185
	v_add_f32_e32 v26, v26, v186
	v_add_f32_e32 v27, v27, v187
	v_add_f32_e32 v28, v28, v188
	v_add_f32_e32 v29, v29, v189
	v_add_f32_e32 v30, v30, v190
	v_add_f32_e32 v31, v31, v191
	v_add_f32_e32 v32, v32, v198
	v_add_f32_e32 v33, v33, v199
	v_add_f32_e32 v34, v34, v200
	v_add_f32_e32 v35, v35, v201
	v_add_f32_e32 v36, v36, v202
	v_add_f32_e32 v37, v37, v203
	v_add_f32_e32 v38, v38, v204
	v_add_f32_e32 v39, v39, v205
	v_add_f32_e32 v40, v40, v206
	v_add_f32_e32 v41, v41, v207
	v_add_f32_e32 v42, v42, v208
	v_add_f32_e32 v43, v43, v209
	global_load_dwordx4 v[160:163], v152, s[38:39]
	s_add_u32 s38, s38, 0x2000
	s_addc_u32 s39, s39, 0
	global_load_dwordx4 v[164:167], v152, s[38:39]
	s_add_u32 s38, s38, 0x2000
	s_addc_u32 s39, s39, 0
	global_load_dwordx4 v[168:171], v152, s[38:39]
	s_add_u32 s38, s38, 0x2000
	s_addc_u32 s39, s39, 0
	global_load_dwordx4 v[172:175], v152, s[38:39]
	s_add_u32 s38, s38, 0x2000
	s_addc_u32 s39, s39, 0
	global_load_dwordx4 v[176:179], v152, s[38:39]
	s_add_u32 s38, s38, 0x2000
	s_addc_u32 s39, s39, 0
	global_load_dwordx4 v[180:183], v152, s[38:39]
	s_add_u32 s38, s38, 0x2000
	s_addc_u32 s39, s39, 0
	global_load_dwordx4 v[184:187], v152, s[38:39]
	s_add_u32 s38, s38, 0x2000
	s_addc_u32 s39, s39, 0
	global_load_dwordx4 v[188:191], v152, s[38:39]
	s_add_u32 s38, s38, 0x2000
	s_addc_u32 s39, s39, 0
	global_load_dwordx4 v[198:201], v152, s[38:39]
	s_add_u32 s38, s38, 0x2000
	s_addc_u32 s39, s39, 0
	global_load_dwordx4 v[202:205], v152, s[38:39]
	s_add_u32 s38, s38, 0x2000
	s_addc_u32 s39, s39, 0
	global_load_dwordx4 v[206:209], v152, s[38:39]
	s_add_u32 s38, s38, 0x2000
	s_addc_u32 s39, s39, 0
	s_waitcnt vmcnt(0)
; #define PG8_BAR __builtin_amdgcn_s_barrier()
; template <class Epi, class Sched, bool ALIGN_EPI = false, bool SP2 = false>
; __device__ __forceinline__ void gemm_phase(PG8_LAS unsigned char* lds, const Gemm g, const Sched& S, const Epi& E) {
;     ...
;         if constexpr (ALIGN_EPI) { if (wr == 0) PG8_BAR; }
;         if constexpr (!Epi::AFTER_DRAIN) { E(acc, cur, wr, wc, fr, fq); S.done(cur); }
	v_add_f32_e32 v44, v44, v160
	v_add_f32_e32 v45, v45, v161
	v_add_f32_e32 v46, v46, v162
	v_add_f32_e32 v47, v47, v163
	v_add_f32_e32 v48, v48, v164
	v_add_f32_e32 v49, v49, v165
	v_add_f32_e32 v50, v50, v166
	v_add_f32_e32 v51, v51, v167
	v_add_f32_e32 v52, v52, v168
	v_add_f32_e32 v53, v53, v169
	v_add_f32_e32 v54, v54, v170
	v_add_f32_e32 v55, v55, v171
	v_add_f32_e32 v56, v56, v172
	v_add_f32_e32 v57, v57, v173
	v_add_f32_e32 v58, v58, v174
	v_add_f32_e32 v59, v59, v175
	v_add_f32_e32 v60, v60, v176
	v_add_f32_e32 v61, v61, v177
	v_add_f32_e32 v62, v62, v178
	v_add_f32_e32 v63, v63, v179
	v_add_f32_e32 v64, v64, v180
	v_add_f32_e32 v65, v65, v181
	v_add_f32_e32 v66, v66, v182
	v_add_f32_e32 v67, v67, v183
	v_add_f32_e32 v68, v68, v184
	v_add_f32_e32 v69, v69, v185
	v_add_f32_e32 v70, v70, v186
	v_add_f32_e32 v71, v71, v187
	v_add_f32_e32 v72, v72, v188
	v_add_f32_e32 v73, v73, v189
	v_add_f32_e32 v74, v74, v190
	v_add_f32_e32 v75, v75, v191
	v_add_f32_e32 v76, v76, v198
	v_add_f32_e32 v77, v77, v199
	v_add_f32_e32 v78, v78, v200
	v_add_f32_e32 v79, v79, v201
	v_add_f32_e32 v80, v80, v202
	v_add_f32_e32 v81, v81, v203
	v_add_f32_e32 v82, v82, v204
	v_add_f32_e32 v83, v83, v205
	v_add_f32_e32 v84, v84, v206
	v_add_f32_e32 v85, v85, v207
	v_add_f32_e32 v86, v86, v208
	v_add_f32_e32 v87, v87, v209
	global_load_dwordx4 v[160:163], v152, s[38:39]
	s_add_u32 s38, s38, 0x2000
	s_addc_u32 s39, s39, 0
	global_load_dwordx4 v[164:167], v152, s[38:39]
	s_add_u32 s38, s38, 0x2000
	s_addc_u32 s39, s39, 0
	global_load_dwordx4 v[168:171], v152, s[38:39]
	s_add_u32 s38, s38, 0x2000
	s_addc_u32 s39, s39, 0
	global_load_dwordx4 v[172:175], v152, s[38:39]
	s_add_u32 s38, s38, 0x2000
	s_addc_u32 s39, s39, 0
	global_load_dwordx4 v[176:179], v152, s[38:39]
	s_add_u32 s38, s38, 0x2000
	s_addc_u32 s39, s39, 0
	global_load_dwordx4 v[180:183], v152, s[38:39]
	s_add_u32 s38, s38, 0x2000
	s_addc_u32 s39, s39, 0
	global_load_dwordx4 v[184:187], v152, s[38:39]
	s_add_u32 s38, s38, 0x2000
	s_addc_u32 s39, s39, 0
	global_load_dwordx4 v[188:191], v152, s[38:39]
	s_add_u32 s38, s38, 0x2000
	s_addc_u32 s39, s39, 0
	global_load_dwordx4 v[198:201], v152, s[38:39]
	s_add_u32 s38, s38, 0x2000
	s_addc_u32 s39, s39, 0
	global_load_dwordx4 v[202:205], v152, s[38:39]
	s_add_u32 s38, s38, 0x2000
	s_addc_u32 s39, s39, 0
	s_waitcnt vmcnt(0)
	v_add_f32_e32 v88, v88, v160
	v_add_f32_e32 v89, v89, v161
	v_add_f32_e32 v90, v90, v162
	v_add_f32_e32 v91, v91, v163
	v_add_f32_e32 v92, v92, v164
	v_add_f32_e32 v93, v93, v165
	v_add_f32_e32 v94, v94, v166
	v_add_f32_e32 v95, v95, v167
	v_add_f32_e32 v96, v96, v168
	v_add_f32_e32 v97, v97, v169
	v_add_f32_e32 v98, v98, v170
	v_add_f32_e32 v99, v99, v171
	v_add_f32_e32 v100, v100, v172
	v_add_f32_e32 v101, v101, v173
	v_add_f32_e32 v102, v102, v174
	v_add_f32_e32 v103, v103, v175
	v_add_f32_e32 v104, v104, v176
	v_add_f32_e32 v105, v105, v177
	v_add_f32_e32 v106, v106, v178
	v_add_f32_e32 v107, v107, v179
	v_add_f32_e32 v108, v108, v180
	v_add_f32_e32 v109, v109, v181
	v_add_f32_e32 v110, v110, v182
	v_add_f32_e32 v111, v111, v183
	v_add_f32_e32 v112, v112, v184
	v_add_f32_e32 v113, v113, v185
	v_add_f32_e32 v114, v114, v186
	v_add_f32_e32 v115, v115, v187
	v_add_f32_e32 v116, v116, v188
	v_add_f32_e32 v117, v117, v189
	v_add_f32_e32 v118, v118, v190
	v_add_f32_e32 v119, v119, v191
	v_add_f32_e32 v120, v120, v198
	v_add_f32_e32 v121, v121, v199
	v_add_f32_e32 v122, v122, v200
	v_add_f32_e32 v123, v123, v201
	v_add_f32_e32 v124, v124, v202
	v_add_f32_e32 v125, v125, v203
	v_add_f32_e32 v126, v126, v204
	v_add_f32_e32 v127, v127, v205
	global_load_dwordx4 v[160:163], v152, s[38:39]
	s_add_u32 s38, s38, 0x2000
	s_addc_u32 s39, s39, 0
	global_load_dwordx4 v[164:167], v152, s[38:39]
	s_add_u32 s38, s38, 0x2000
	s_addc_u32 s39, s39, 0
	global_load_dwordx4 v[168:171], v152, s[38:39]
	s_add_u32 s38, s38, 0x2000
	s_addc_u32 s39, s39, 0
	global_load_dwordx4 v[172:175], v152, s[38:39]
	s_add_u32 s38, s38, 0x2000
	s_addc_u32 s39, s39, 0
	global_load_dwordx4 v[176:179], v152, s[38:39]
	s_add_u32 s38, s38, 0x2000
	s_addc_u32 s39, s39, 0
	global_load_dwordx4 v[180:183], v152, s[38:39]
	s_add_u32 s38, s38, 0x2000
	s_addc_u32 s39, s39, 0
	global_load_dwordx4 v[184:187], v152, s[38:39]
	s_add_u32 s38, s38, 0x2000
	s_addc_u32 s39, s39, 0
	global_load_dwordx4 v[188:191], v152, s[38:39]
	s_add_u32 s38, s38, 0x2000
	s_addc_u32 s39, s39, 0
	global_load_dwordx4 v[198:201], v152, s[38:39]
	s_add_u32 s38, s38, 0x2000
	s_addc_u32 s39, s39, 0
	global_load_dwordx4 v[202:205], v152, s[38:39]
	s_add_u32 s38, s38, 0x2000
	s_addc_u32 s39, s39, 0
	global_load_dwordx4 v[206:209], v152, s[38:39]
	s_add_u32 s38, s38, 0x2000
	s_addc_u32 s39, s39, 0
	s_waitcnt vmcnt(0)
; #define PG8_BAR __builtin_amdgcn_s_barrier()
; template <class Epi, class Sched, bool ALIGN_EPI = false, bool SP2 = false>
; __device__ __forceinline__ void gemm_phase(PG8_LAS unsigned char* lds, const Gemm g, const Sched& S, const Epi& E) {
;     ...
;         if constexpr (ALIGN_EPI) { if (wr == 0) PG8_BAR; }
;         if constexpr (!Epi::AFTER_DRAIN) { E(acc, cur, wr, wc, fr, fq); S.done(cur); }
	v_add_f32_e32 v0, v0, v160
	v_add_f32_e32 v1, v1, v161
	v_add_f32_e32 v2, v2, v162
	v_add_f32_e32 v3, v3, v163
	v_add_f32_e32 v4, v4, v164
	v_add_f32_e32 v5, v5, v165
	v_add_f32_e32 v6, v6, v166
	v_add_f32_e32 v7, v7, v167
	v_add_f32_e32 v8, v8, v168
	v_add_f32_e32 v9, v9, v169
	v_add_f32_e32 v10, v10, v170
	v_add_f32_e32 v11, v11, v171
	v_add_f32_e32 v12, v12, v172
	v_add_f32_e32 v13, v13, v173
	v_add_f32_e32 v14, v14, v174
	v_add_f32_e32 v15, v15, v175
	v_add_f32_e32 v16, v16, v176
	v_add_f32_e32 v17, v17, v177
	v_add_f32_e32 v18, v18, v178
	v_add_f32_e32 v19, v19, v179
	v_add_f32_e32 v20, v20, v180
	v_add_f32_e32 v21, v21, v181
	v_add_f32_e32 v22, v22, v182
	v_add_f32_e32 v23, v23, v183
	v_add_f32_e32 v24, v24, v184
	v_add_f32_e32 v25, v25, v185
	v_add_f32_e32 v26, v26, v186
	v_add_f32_e32 v27, v27, v187
	v_add_f32_e32 v28, v28, v188
	v_add_f32_e32 v29, v29, v189
	v_add_f32_e32 v30, v30, v190
	v_add_f32_e32 v31, v31, v191
	v_add_f32_e32 v32, v32, v198
	v_add_f32_e32 v33, v33, v199
	v_add_f32_e32 v34, v34, v200
	v_add_f32_e32 v35, v35, v201
	v_add_f32_e32 v36, v36, v202
	v_add_f32_e32 v37, v37, v203
	v_add_f32_e32 v38, v38, v204
	v_add_f32_e32 v39, v39, v205
	v_add_f32_e32 v40, v40, v206
	v_add_f32_e32 v41, v41, v207
	v_add_f32_e32 v42, v42, v208
	v_add_f32_e32 v43, v43, v209
	global_load_dwordx4 v[160:163], v152, s[38:39]
	s_add_u32 s38, s38, 0x2000
	s_addc_u32 s39, s39, 0
	global_load_dwordx4 v[164:167], v152, s[38:39]
	s_add_u32 s38, s38, 0x2000
	s_addc_u32 s39, s39, 0
	global_load_dwordx4 v[168:171], v152, s[38:39]
	s_add_u32 s38, s38, 0x2000
	s_addc_u32 s39, s39, 0
	global_load_dwordx4 v[172:175], v152, s[38:39]
	s_add_u32 s38, s38, 0x2000
	s_addc_u32 s39, s39, 0
	global_load_dwordx4 v[176:179], v152, s[38:39]
	s_add_u32 s38, s38, 0x2000
	s_addc_u32 s39, s39, 0
	global_load_dwordx4 v[180:183], v152, s[38:39]
	s_add_u32 s38, s38, 0x2000
	s_addc_u32 s39, s39, 0
	global_load_dwordx4 v[184:187], v152, s[38:39]
	s_add_u32 s38, s38, 0x2000
	s_addc_u32 s39, s39, 0
	global_load_dwordx4 v[188:191], v152, s[38:39]
	s_add_u32 s38, s38, 0x2000
	s_addc_u32 s39, s39, 0
	global_load_dwordx4 v[198:201], v152, s[38:39]
	s_add_u32 s38, s38, 0x2000
	s_addc_u32 s39, s39, 0
	global_load_dwordx4 v[202:205], v152, s[38:39]
	s_add_u32 s38, s38, 0x2000
	s_addc_u32 s39, s39, 0
	global_load_dwordx4 v[206:209], v152, s[38:39]
	s_add_u32 s38, s38, 0x2000
	s_addc_u32 s39, s39, 0
	s_waitcnt vmcnt(0)
	v_add_f32_e32 v44, v44, v160
	v_add_f32_e32 v45, v45, v161
	v_add_f32_e32 v46, v46, v162
	v_add_f32_e32 v47, v47, v163
	v_add_f32_e32 v48, v48, v164
	v_add_f32_e32 v49, v49, v165
	v_add_f32_e32 v50, v50, v166
	v_add_f32_e32 v51, v51, v167
	v_add_f32_e32 v52, v52, v168
	v_add_f32_e32 v53, v53, v169
	v_add_f32_e32 v54, v54, v170
	v_add_f32_e32 v55, v55, v171
	v_add_f32_e32 v56, v56, v172
	v_add_f32_e32 v57, v57, v173
	v_add_f32_e32 v58, v58, v174
	v_add_f32_e32 v59, v59, v175
	v_add_f32_e32 v60, v60, v176
	v_add_f32_e32 v61, v61, v177
	v_add_f32_e32 v62, v62, v178
	v_add_f32_e32 v63, v63, v179
	v_add_f32_e32 v64, v64, v180
	v_add_f32_e32 v65, v65, v181
	v_add_f32_e32 v66, v66, v182
	v_add_f32_e32 v67, v67, v183
	v_add_f32_e32 v68, v68, v184
	v_add_f32_e32 v69, v69, v185
	v_add_f32_e32 v70, v70, v186
	v_add_f32_e32 v71, v71, v187
	v_add_f32_e32 v72, v72, v188
	v_add_f32_e32 v73, v73, v189
	v_add_f32_e32 v74, v74, v190
	v_add_f32_e32 v75, v75, v191
	v_add_f32_e32 v76, v76, v198
	v_add_f32_e32 v77, v77, v199
	v_add_f32_e32 v78, v78, v200
	v_add_f32_e32 v79, v79, v201
	v_add_f32_e32 v80, v80, v202
	v_add_f32_e32 v81, v81, v203
	v_add_f32_e32 v82, v82, v204
	v_add_f32_e32 v83, v83, v205
	v_add_f32_e32 v84, v84, v206
	v_add_f32_e32 v85, v85, v207
	v_add_f32_e32 v86, v86, v208
	v_add_f32_e32 v87, v87, v209
	global_load_dwordx4 v[160:163], v152, s[38:39]
	s_add_u32 s38, s38, 0x2000
	s_addc_u32 s39, s39, 0
	global_load_dwordx4 v[164:167], v152, s[38:39]
	s_add_u32 s38, s38, 0x2000
	s_addc_u32 s39, s39, 0
	global_load_dwordx4 v[168:171], v152, s[38:39]
	s_add_u32 s38, s38, 0x2000
	s_addc_u32 s39, s39, 0
	global_load_dwordx4 v[172:175], v152, s[38:39]
	s_add_u32 s38, s38, 0x2000
	s_addc_u32 s39, s39, 0
	global_load_dwordx4 v[176:179], v152, s[38:39]
	s_add_u32 s38, s38, 0x2000
	s_addc_u32 s39, s39, 0
	global_load_dwordx4 v[180:183], v152, s[38:39]
	s_add_u32 s38, s38, 0x2000
	s_addc_u32 s39, s39, 0
	global_load_dwordx4 v[184:187], v152, s[38:39]
	s_add_u32 s38, s38, 0x2000
	s_addc_u32 s39, s39, 0
	global_load_dwordx4 v[188:191], v152, s[38:39]
	s_add_u32 s38, s38, 0x2000
	s_addc_u32 s39, s39, 0
	global_load_dwordx4 v[198:201], v152, s[38:39]
	s_add_u32 s38, s38, 0x2000
	s_addc_u32 s39, s39, 0
	global_load_dwordx4 v[202:205], v152, s[38:39]
	s_add_u32 s38, s38, 0x2000
	s_addc_u32 s39, s39, 0
	s_waitcnt vmcnt(0)
	v_add_f32_e32 v88, v88, v160
	v_add_f32_e32 v89, v89, v161
	v_add_f32_e32 v90, v90, v162
	v_add_f32_e32 v91, v91, v163
	v_add_f32_e32 v92, v92, v164
	v_add_f32_e32 v93, v93, v165
	v_add_f32_e32 v94, v94, v166
	v_add_f32_e32 v95, v95, v167
	v_add_f32_e32 v96, v96, v168
	v_add_f32_e32 v97, v97, v169
	v_add_f32_e32 v98, v98, v170
	v_add_f32_e32 v99, v99, v171
	v_add_f32_e32 v100, v100, v172
	v_add_f32_e32 v101, v101, v173
	v_add_f32_e32 v102, v102, v174
	v_add_f32_e32 v103, v103, v175
	v_add_f32_e32 v104, v104, v176
	v_add_f32_e32 v105, v105, v177
	v_add_f32_e32 v106, v106, v178
	v_add_f32_e32 v107, v107, v179
	v_add_f32_e32 v108, v108, v180
	v_add_f32_e32 v109, v109, v181
	v_add_f32_e32 v110, v110, v182
	v_add_f32_e32 v111, v111, v183
	v_add_f32_e32 v112, v112, v184
	v_add_f32_e32 v113, v113, v185
	v_add_f32_e32 v114, v114, v186
	v_add_f32_e32 v115, v115, v187
	v_add_f32_e32 v116, v116, v188
	v_add_f32_e32 v117, v117, v189
	v_add_f32_e32 v118, v118, v190
	v_add_f32_e32 v119, v119, v191
	v_add_f32_e32 v120, v120, v198
	v_add_f32_e32 v121, v121, v199
	v_add_f32_e32 v122, v122, v200
	v_add_f32_e32 v123, v123, v201
	v_add_f32_e32 v124, v124, v202
	v_add_f32_e32 v125, v125, v203
	v_add_f32_e32 v126, v126, v204
	v_add_f32_e32 v127, v127, v205

; #define PG8_BAR __builtin_amdgcn_s_barrier()
; template <class Epi, class Sched, bool ALIGN_EPI = false, bool SP2 = false>
; __device__ __forceinline__ void gemm_phase(PG8_LAS unsigned char* lds, const Gemm g, const Sched& S, const Epi& E) {
;     ...
;         if (!has_next) break;
; #pragma unroll
;         for (int a = 0; a < 2; ++a)
; #pragma unroll
;             for (int b = 0; b < 2; ++b)
; #pragma unroll
;                 for (int m = 0; m < 4; ++m)
; #pragma unroll
;                     for (int n = 0; n < 2; ++n) acc[a][b][m][n] = (f32x4){0.f, 0.f, 0.f, 0.f};
;         cur = nxt; cA = nA; cB = nB; ++ui;
;         if constexpr (ALIGN_EPI) { if (wr == 1) PG8_BAR; }
;     }
.Lup_ep_done:
	s_andn2_b64 vcc, exec, s[10:11]
	s_mov_b64 s[4:5], -1
	s_cbranch_vccnz .LBB0_1071
	s_andn2_b64 vcc, exec, s[26:27]
	s_cbranch_vccnz .LBB0_1070
	s_barrier
	s_branch .LBB0_1070
